# static priority raise (s_setprio 3) for the diff-latent attention waves on top of the XCD-affine mix assignment
# speedup vs baseline: 1.0079x; 1.0079x over previous
.LBB0_427:
	s_setprio 3
	s_bitcmp1_b32 s18, 0
	s_cselect_b32 s98, 0x4800, 0
	v_or_b32_e32 v210, s98, v166
	v_add_u32_e32 v210, v210, v171
	ds_read_b128 v[4:7], v210
	ds_read_b128 v[8:11], v210 offset:32
	s_cmpk_gt_u32 s18, 0x41
	s_cbranch_scc1 .LBB0_431
	s_mov_b64 s[8:9], 0x100
	s_cmp_lt_u32 s18, 2
	s_mov_b64 s[4:5], s[0:1]
	s_mov_b64 s[6:7], s[2:3]
	s_cbranch_scc1 .LBB0_430
	s_lshl_b64 s[4:5], s[56:57], 7
	s_add_u32 s6, s15, s4
	s_addc_u32 s7, s16, s5
	s_lshl_b64 s[4:5], s[56:57], 1
	s_add_u32 s4, s13, s4
	s_addc_u32 s5, s14, s5
	s_mov_b64 s[8:9], 0x1000

.LBB0_435:
	v_pk_fma_f32 v[96:97], v[96:97], s[58:59], v[210:211] op_sel_hi:[1,0,0] neg_lo:[0,0,1] neg_hi:[0,0,1]
	v_pk_fma_f32 v[98:99], v[98:99], s[58:59], v[210:211] op_sel_hi:[1,0,0] neg_lo:[0,0,1] neg_hi:[0,0,1]
	v_exp_f32_e32 v96, v96
	v_exp_f32_e32 v97, v97
	v_exp_f32_e32 v98, v98
	v_exp_f32_e32 v99, v99
	v_pk_fma_f32 v[100:101], v[100:101], s[58:59], v[210:211] op_sel_hi:[1,0,0] neg_lo:[0,0,1] neg_hi:[0,0,1]
	v_pk_fma_f32 v[102:103], v[102:103], s[58:59], v[210:211] op_sel_hi:[1,0,0] neg_lo:[0,0,1] neg_hi:[0,0,1]
	v_exp_f32_e32 v100, v100
	v_exp_f32_e32 v101, v101
	v_exp_f32_e32 v102, v102
	v_exp_f32_e32 v103, v103
	v_pk_fma_f32 v[104:105], v[104:105], s[58:59], v[210:211] op_sel_hi:[1,0,0] neg_lo:[0,0,1] neg_hi:[0,0,1]
	v_pk_add_f32 v[238:239], v[96:97], 0 op_sel_hi:[1,0]
	v_exp_f32_e32 v104, v104
	v_exp_f32_e32 v105, v105
	v_pk_fma_f32 v[106:107], v[106:107], s[58:59], v[210:211] op_sel_hi:[1,0,0] neg_lo:[0,0,1] neg_hi:[0,0,1]
	v_pk_add_f32 v[238:239], v[98:99], v[238:239]
	v_exp_f32_e32 v106, v106
	v_exp_f32_e32 v107, v107
	v_pk_fma_f32 v[108:109], v[108:109], s[58:59], v[210:211] op_sel_hi:[1,0,0] neg_lo:[0,0,1] neg_hi:[0,0,1]
	v_pk_add_f32 v[238:239], v[100:101], v[238:239]
	v_exp_f32_e32 v108, v108
	v_exp_f32_e32 v109, v109
	v_pk_fma_f32 v[110:111], v[110:111], s[58:59], v[210:211] op_sel_hi:[1,0,0] neg_lo:[0,0,1] neg_hi:[0,0,1]
	v_pk_add_f32 v[238:239], v[102:103], v[238:239]
	v_exp_f32_e32 v110, v110
	v_exp_f32_e32 v111, v111
	v_pk_fma_f32 v[80:81], v[80:81], s[58:59], v[210:211] op_sel_hi:[1,0,0] neg_lo:[0,0,1] neg_hi:[0,0,1]
	v_pk_add_f32 v[238:239], v[104:105], v[238:239]
	v_exp_f32_e32 v240, v80
	v_exp_f32_e32 v241, v81
	v_pk_fma_f32 v[80:81], v[82:83], s[58:59], v[210:211] op_sel_hi:[1,0,0] neg_lo:[0,0,1] neg_hi:[0,0,1]
	v_pk_add_f32 v[238:239], v[106:107], v[238:239]
	v_exp_f32_e32 v242, v80
	v_exp_f32_e32 v243, v81
	v_pk_fma_f32 v[80:81], v[84:85], s[58:59], v[210:211] op_sel_hi:[1,0,0] neg_lo:[0,0,1] neg_hi:[0,0,1]
	v_pk_add_f32 v[238:239], v[108:109], v[238:239]
	v_exp_f32_e32 v84, v80
	v_exp_f32_e32 v85, v81
	v_pk_add_f32 v[80:81], v[110:111], v[238:239]
	v_cvt_pk_bf16_f32 v82, v100, v101
	v_pk_add_f32 v[80:81], v[240:241], v[80:81]
	v_cvt_pk_bf16_f32 v83, v102, v103
	v_pk_add_f32 v[80:81], v[242:243], v[80:81]
	s_add_i32 s56, s56, 64
	v_pk_add_f32 v[238:239], v[84:85], v[80:81]
	v_pk_fma_f32 v[80:81], v[86:87], s[58:59], v[210:211] op_sel_hi:[1,0,0] neg_lo:[0,0,1] neg_hi:[0,0,1]
	s_add_u32 s0, s0, 0x80
	v_exp_f32_e32 v86, v80
	v_exp_f32_e32 v87, v81
	v_cvt_pk_bf16_f32 v80, v96, v97
	v_cvt_pk_bf16_f32 v81, v98, v99
	s_addc_u32 s1, s1, 0
	v_pk_add_f32 v[96:97], v[86:87], v[238:239]
	v_mfma_f32_32x32x16_bf16 v[64:79], v[6:9], v[80:83], v[64:79]
	v_fma_f32 v6, v88, s58, -v210
	v_fma_f32 v7, v89, s58, -v210
	v_cvt_pk_bf16_f32 v8, v108, v109
	v_exp_f32_e32 v88, v6
	v_exp_f32_e32 v89, v7
	v_pk_fma_f32 v[6:7], v[90:91], s[58:59], v[210:211] op_sel_hi:[1,0,0] neg_lo:[0,0,1] neg_hi:[0,0,1]
	v_cvt_pk_bf16_f32 v9, v110, v111
	v_exp_f32_e32 v90, v6
	v_mfma_f32_32x32x16_bf16 v[32:47], v[10:13], v[80:83], v[32:47]
	v_exp_f32_e32 v91, v7
	v_pk_fma_f32 v[6:7], v[92:93], s[58:59], v[210:211] op_sel_hi:[1,0,0] neg_lo:[0,0,1] neg_hi:[0,0,1]
	s_add_u32 s2, s2, 0x2000
	v_exp_f32_e32 v10, v6
	v_exp_f32_e32 v11, v7
	v_cvt_pk_bf16_f32 v6, v104, v105
	v_cvt_pk_bf16_f32 v7, v106, v107
	s_addc_u32 s3, s3, 0
	s_cmpk_lg_i32 s17, 0x44
	v_mfma_f32_32x32x16_bf16 v[64:79], v[2:5], v[6:9], v[64:79]
	v_cvt_pk_bf16_f32 v4, v240, v241
	v_cvt_pk_bf16_f32 v5, v242, v243
	v_fma_f32 v2, v94, s58, -v210
	v_fma_f32 v3, v95, s58, -v210
	v_exp_f32_e32 v12, v2
	v_exp_f32_e32 v13, v3
	v_pk_add_f32 v[2:3], v[88:89], v[96:97]
	v_mfma_f32_32x32x16_bf16 v[32:47], v[144:147], v[6:9], v[32:47]
	v_add_f32_e64 v8, v180, 0
	v_add_f32_e64 v9, v181, 0
	v_cvt_pk_bf16_f32 v6, v84, v85
	v_cvt_pk_bf16_f32 v7, v86, v87
	v_add_f32_e64 v8, v178, v8
	v_add_f32_e64 v9, v179, v9
	v_pk_add_f32 v[2:3], v[90:91], v[2:3]
	v_pk_add_f32 v[8:9], v[182:183], v[8:9]
	v_pk_add_f32 v[2:3], v[10:11], v[2:3]
	v_mfma_f32_32x32x16_bf16 v[64:79], v[148:151], v[4:7], v[64:79]
	v_add_f32_e64 v8, v184, v8
	v_add_f32_e64 v9, v185, v9
	v_add_f32_e64 v2, v12, v2
	v_add_f32_e64 v3, v13, v3
	v_add_f32_e64 v8, v186, v8
	v_add_f32_e64 v9, v187, v9
	v_add_f32_e32 v3, v2, v3
	v_pk_add_f32 v[8:9], v[188:189], v[8:9]
	v_fmac_f32_e32 v3, v236, v212
	v_pk_add_f32 v[8:9], v[194:195], v[8:9]
	v_mfma_f32_32x32x16_bf16 v[32:47], v[152:155], v[4:7], v[32:47]
	v_add_f32_e64 v8, v200, v8
	v_add_f32_e64 v9, v201, v9
	v_cvt_pk_bf16_f32 v6, v88, v89
	v_add_f32_e64 v4, v198, v8
	v_add_f32_e64 v5, v199, v9
	v_cvt_pk_bf16_f32 v7, v90, v91
	v_pk_add_f32 v[4:5], v[204:205], v[4:5]
	v_cvt_pk_bf16_f32 v8, v10, v11
	v_cvt_pk_bf16_f32 v9, v12, v13
	v_pk_add_f32 v[4:5], v[208:209], v[4:5]
	s_barrier
	v_mfma_f32_32x32x16_bf16 v[64:79], v[156:159], v[6:9], v[64:79]
	v_add_f32_e64 v4, v190, v4
	v_add_f32_e64 v5, v191, v5
	v_add_f32_e64 v4, v192, v4
	v_add_f32_e64 v5, v193, v5
	v_add_f32_e64 v4, v196, v4
	v_add_f32_e64 v5, v197, v5
	v_pk_add_f32 v[4:5], v[202:203], v[4:5]
	v_mfma_f32_32x32x16_bf16 v[32:47], v[160:163], v[6:9], v[32:47]
	v_add_f32_e64 v4, v206, v4
	v_add_f32_e64 v5, v207, v5
	v_add_f32_e32 v4, v4, v5
	v_fmac_f32_e32 v4, v15, v14
	s_cbranch_scc1 .LBB0_425
	s_setprio 0
	ds_bpermute_b32 v0, v167, v4
	s_movk_i32 s0, 0x90
	v_mul_lo_u32 v15, v234, s0
	v_readlane_b32 s2, v255, 9
	v_readlane_b32 s3, v255, 10
	s_waitcnt lgkmcnt(0)
	v_add_f32_e32 v0, v4, v0
	v_div_scale_f32 v2, s[0:1], v0, v0, 1.0
	v_rcp_f32_e32 v4, v2
	s_mov_b64 s[6:7], -1
	v_fma_f32 v5, -v2, v4, 1.0
	v_fmac_f32_e32 v4, v5, v4
	v_div_scale_f32 v5, vcc, 1.0, v0, 1.0
	v_mul_f32_e32 v6, v5, v4
	v_fma_f32 v7, -v2, v6, v5
	v_fmac_f32_e32 v6, v7, v4
	v_fma_f32 v2, -v2, v6, v5
	v_div_fmas_f32 v2, v2, v4, v6
	v_div_fixup_f32 v0, v2, v0, 1.0
	ds_bpermute_b32 v2, v167, v3
	s_waitcnt lgkmcnt(0)
	v_add_f32_e32 v2, v3, v2
	v_div_scale_f32 v3, s[0:1], v2, v2, 1.0
	v_rcp_f32_e32 v4, v3
	v_readlane_b32 s0, v255, 7
	v_readlane_b32 s1, v255, 8
	v_fma_f32 v5, -v3, v4, 1.0
	v_fmac_f32_e32 v4, v5, v4
	v_div_scale_f32 v5, vcc, 1.0, v2, 1.0
	v_mul_f32_e32 v6, v5, v4
	v_fma_f32 v7, -v3, v6, v5
	v_fmac_f32_e32 v6, v7, v4
	v_fma_f32 v3, -v3, v6, v5
	v_div_fmas_f32 v3, v3, v4, v6
	v_div_fixup_f32 v14, v3, v2, 1.0
	global_load_dwordx4 v[2:5], v1, s[0:1] offset:48
	global_load_dwordx4 v[6:9], v1, s[0:1] offset:32
	global_load_dwordx4 v[10:13], v1, s[0:1] offset:16
	global_load_dwordx4 v[80:83], v1, s[0:1]
	global_load_dwordx4 v[84:87], v1, s[0:1] offset:176
	global_load_dwordx4 v[88:91], v1, s[0:1] offset:160
	global_load_dwordx4 v[92:95], v1, s[0:1] offset:144
	global_load_dwordx4 v[96:99], v1, s[0:1] offset:128
	global_load_dwordx4 v[100:103], v1, s[0:1] offset:304
	global_load_dwordx4 v[104:107], v1, s[0:1] offset:288
	global_load_dwordx4 v[108:111], v1, s[0:1] offset:272
	global_load_dwordx4 v[112:115], v1, s[0:1] offset:256
	global_load_dwordx4 v[116:119], v1, s[0:1] offset:432
	global_load_dwordx4 v[120:123], v1, s[0:1] offset:416
	global_load_dwordx4 v[124:127], v1, s[0:1] offset:400
	global_load_dwordx4 v[128:131], v1, s[0:1] offset:384
	s_waitcnt vmcnt(8)
	v_fma_f32 v132, v80, v96, 0
	v_fmac_f32_e32 v132, v81, v97
	s_waitcnt vmcnt(0)
	v_fma_f32 v133, v112, v128, 0
	v_fmac_f32_e32 v132, v82, v98
	v_fmac_f32_e32 v133, v113, v129
	v_fmac_f32_e32 v132, v83, v99
	v_fmac_f32_e32 v133, v114, v130
	v_fmac_f32_e32 v132, v10, v92
	v_fmac_f32_e32 v133, v115, v131
	v_fmac_f32_e32 v132, v11, v93
	v_fmac_f32_e32 v133, v108, v124
	v_fmac_f32_e32 v132, v12, v94
	v_fmac_f32_e32 v133, v109, v125
	v_fmac_f32_e32 v132, v13, v95
	v_fmac_f32_e32 v133, v110, v126
	v_fmac_f32_e32 v132, v6, v88
	v_fmac_f32_e32 v133, v111, v127
	v_fmac_f32_e32 v132, v7, v89
	v_fmac_f32_e32 v133, v104, v120
	v_fmac_f32_e32 v132, v8, v90
	v_fmac_f32_e32 v133, v105, v121
	v_fmac_f32_e32 v132, v9, v91
	v_fmac_f32_e32 v133, v106, v122
	v_fmac_f32_e32 v132, v2, v84
	v_fmac_f32_e32 v133, v107, v123
	v_fmac_f32_e32 v132, v3, v85
	v_fmac_f32_e32 v133, v100, v116
	v_fmac_f32_e32 v132, v4, v86
	v_fmac_f32_e32 v133, v101, v117
	v_fmac_f32_e32 v132, v5, v87
	global_load_dwordx4 v[2:5], v1, s[0:1] offset:80
	global_load_dwordx4 v[92:95], v1, s[0:1] offset:64
	global_load_dwordx4 v[6:9], v1, s[0:1] offset:112
	global_load_dwordx4 v[10:13], v1, s[0:1] offset:96
	global_load_dwordx4 v[84:87], v1, s[0:1] offset:208
	global_load_dwordx4 v[104:107], v1, s[0:1] offset:192
	global_load_dwordx4 v[80:83], v1, s[0:1] offset:240
	global_load_dwordx4 v[88:91], v1, s[0:1] offset:224
	v_fmac_f32_e32 v133, v102, v118
	v_fmac_f32_e32 v133, v103, v119
	global_load_dwordx4 v[96:99], v1, s[0:1] offset:336
	global_load_dwordx4 v[120:123], v1, s[0:1] offset:320
	global_load_dwordx4 v[100:103], v1, s[0:1] offset:368
	global_load_dwordx4 v[108:111], v1, s[0:1] offset:352
	global_load_dwordx4 v[116:119], v1, s[0:1] offset:464
	global_load_dwordx4 v[124:127], v1, s[0:1] offset:448
	global_load_dwordx4 v[112:115], v1, s[0:1] offset:496
	global_load_dwordx4 v[128:131], v1, s[0:1] offset:480
	s_mov_b32 s0, 0x7060302
	s_waitcnt vmcnt(10)
	v_fmac_f32_e32 v132, v92, v104
	v_fmac_f32_e32 v132, v93, v105
	v_fmac_f32_e32 v132, v94, v106
	s_waitcnt vmcnt(2)
	v_fmac_f32_e32 v133, v120, v124
	v_fmac_f32_e32 v133, v121, v125
	v_fmac_f32_e32 v132, v95, v107
	v_fmac_f32_e32 v133, v122, v126
	v_fmac_f32_e32 v132, v2, v84
	v_fmac_f32_e32 v133, v123, v127
	v_fmac_f32_e32 v132, v3, v85
	v_fmac_f32_e32 v133, v96, v116
	v_fmac_f32_e32 v132, v4, v86
	v_fmac_f32_e32 v133, v97, v117
	v_fmac_f32_e32 v132, v5, v87
	v_pk_mul_f32 v[2:3], v[10:11], v[88:89]
	v_fmac_f32_e32 v133, v98, v118
	v_add_f32_e32 v2, v132, v2
	v_fmac_f32_e32 v133, v99, v119
	v_add_f32_e32 v4, v2, v3
	s_waitcnt vmcnt(0)
	v_pk_mul_f32 v[2:3], v[108:109], v[128:129]
	s_nop 0
	v_add_f32_e32 v2, v133, v2
	v_add_f32_e32 v5, v2, v3
	v_pk_mul_f32 v[2:3], v[12:13], v[90:91]
	s_nop 0
	v_add_f32_e32 v2, v4, v2
	v_add_f32_e32 v4, v2, v3
	v_pk_mul_f32 v[2:3], v[110:111], v[130:131]
	s_nop 0
	v_add_f32_e32 v2, v5, v2
	v_add_f32_e32 v5, v2, v3
	v_pk_mul_f32 v[2:3], v[6:7], v[80:81]
	v_add3_u32 v81, v15, v171, v235
	v_add_f32_e32 v2, v4, v2
	v_add_f32_e32 v4, v2, v3
	v_pk_mul_f32 v[2:3], v[100:101], v[112:113]
	s_nop 0
	v_add_f32_e32 v2, v5, v2
	v_add_f32_e32 v5, v2, v3
	v_pk_mul_f32 v[2:3], v[8:9], v[82:83]
	s_nop 0
	v_add_f32_e32 v2, v4, v2
	v_add_f32_e32 v4, v2, v3
	v_pk_mul_f32 v[2:3], v[102:103], v[114:115]
	s_nop 0
	v_add_f32_e32 v2, v5, v2
	v_add_f32_e32 v2, v2, v3
	v_mul_f32_e32 v3, 0x3fb8aa3b, v4
	v_mul_f32_e32 v2, 0x3fb8aa3b, v2
	v_exp_f32_e32 v3, v3
	v_exp_f32_e32 v2, v2
	s_nop 0
	v_sub_f32_e32 v2, v3, v2
	v_add_f32_e32 v80, v232, v2
	v_pk_mul_f32 v[4:5], v[64:65], v[80:81] op_sel_hi:[1,0]
	v_pk_mul_f32 v[2:3], v[66:67], v[80:81] op_sel_hi:[1,0]
	v_pk_mul_f32 v[4:5], v[14:15], v[4:5] op_sel_hi:[0,1]
	v_pk_fma_f32 v[66:67], v[48:49], v[0:1], v[4:5] op_sel_hi:[1,0,1] neg_lo:[0,0,1] neg_hi:[0,0,1]
	v_pk_mul_f32 v[2:3], v[14:15], v[2:3] op_sel_hi:[0,1]
	v_mul_f32_e32 v82, v67, v67
	v_pk_fma_f32 v[64:65], v[50:51], v[0:1], v[2:3] op_sel_hi:[1,0,1] neg_lo:[0,0,1] neg_hi:[0,0,1]
	v_fmac_f32_e32 v82, v66, v66
	global_load_dwordx4 v[2:5], v166, s[2:3]
	v_pk_mul_f32 v[8:9], v[68:69], v[80:81] op_sel_hi:[1,0]
	v_fmac_f32_e32 v82, v64, v64
	v_pk_mul_f32 v[8:9], v[14:15], v[8:9] op_sel_hi:[0,1]
	v_fmac_f32_e32 v82, v65, v65
	v_pk_mul_f32 v[6:7], v[70:71], v[80:81] op_sel_hi:[1,0]
	v_pk_fma_f32 v[52:53], v[52:53], v[0:1], v[8:9] op_sel_hi:[1,0,1] neg_lo:[0,0,1] neg_hi:[0,0,1]
	v_pk_mul_f32 v[6:7], v[14:15], v[6:7] op_sel_hi:[0,1]
	v_fmac_f32_e32 v82, v52, v52
	v_pk_fma_f32 v[54:55], v[54:55], v[0:1], v[6:7] op_sel_hi:[1,0,1] neg_lo:[0,0,1] neg_hi:[0,0,1]
	v_fmac_f32_e32 v82, v53, v53
	global_load_dwordx4 v[6:9], v166, s[2:3] offset:32
	v_pk_mul_f32 v[12:13], v[72:73], v[80:81] op_sel_hi:[1,0]
	v_fmac_f32_e32 v82, v54, v54
	v_pk_mul_f32 v[12:13], v[14:15], v[12:13] op_sel_hi:[0,1]
	v_fmac_f32_e32 v82, v55, v55
	v_pk_mul_f32 v[10:11], v[74:75], v[80:81] op_sel_hi:[1,0]
	v_pk_fma_f32 v[56:57], v[56:57], v[0:1], v[12:13] op_sel_hi:[1,0,1] neg_lo:[0,0,1] neg_hi:[0,0,1]
	v_pk_mul_f32 v[10:11], v[14:15], v[10:11] op_sel_hi:[0,1]
	v_fmac_f32_e32 v82, v56, v56
	v_pk_fma_f32 v[58:59], v[58:59], v[0:1], v[10:11] op_sel_hi:[1,0,1] neg_lo:[0,0,1] neg_hi:[0,0,1]
	v_fmac_f32_e32 v82, v57, v57
	v_pk_mul_f32 v[50:51], v[76:77], v[80:81] op_sel_hi:[1,0]
	v_fmac_f32_e32 v82, v58, v58
	global_load_dwordx4 v[10:13], v166, s[2:3] offset:64
	v_pk_mul_f32 v[50:51], v[14:15], v[50:51] op_sel_hi:[0,1]
	v_fmac_f32_e32 v82, v59, v59
	v_pk_mul_f32 v[48:49], v[78:79], v[80:81] op_sel_hi:[1,0]
	v_pk_fma_f32 v[60:61], v[60:61], v[0:1], v[50:51] op_sel_hi:[1,0,1] neg_lo:[0,0,1] neg_hi:[0,0,1]
	v_pk_mul_f32 v[48:49], v[14:15], v[48:49] op_sel_hi:[0,1]
	v_fmac_f32_e32 v82, v60, v60
	v_pk_fma_f32 v[62:63], v[62:63], v[0:1], v[48:49] op_sel_hi:[1,0,1] neg_lo:[0,0,1] neg_hi:[0,0,1]
	v_fmac_f32_e32 v82, v61, v61
	v_pk_mul_f32 v[32:33], v[32:33], v[80:81] op_sel_hi:[1,0]
	v_fmac_f32_e32 v82, v62, v62
	global_load_dwordx4 v[48:51], v166, s[2:3] offset:96
	v_pk_mul_f32 v[32:33], v[14:15], v[32:33] op_sel_hi:[0,1]
	v_fmac_f32_e32 v82, v63, v63
	v_pk_mul_f32 v[34:35], v[34:35], v[80:81] op_sel_hi:[1,0]
	v_pk_fma_f32 v[32:33], v[16:17], v[0:1], v[32:33] op_sel_hi:[1,0,1] neg_lo:[0,0,1] neg_hi:[0,0,1]
	v_pk_mul_f32 v[34:35], v[14:15], v[34:35] op_sel_hi:[0,1]
	v_fmac_f32_e32 v82, v32, v32
	v_pk_fma_f32 v[34:35], v[18:19], v[0:1], v[34:35] op_sel_hi:[1,0,1] neg_lo:[0,0,1] neg_hi:[0,0,1]
	v_fmac_f32_e32 v82, v33, v33
	v_pk_mul_f32 v[36:37], v[36:37], v[80:81] op_sel_hi:[1,0]
	v_fmac_f32_e32 v82, v34, v34
	v_pk_mul_f32 v[38:39], v[38:39], v[80:81] op_sel_hi:[1,0]
	v_pk_mul_f32 v[36:37], v[14:15], v[36:37] op_sel_hi:[0,1]
	v_fmac_f32_e32 v82, v35, v35
	global_load_dwordx4 v[16:19], v166, s[2:3] offset:128
	v_pk_mul_f32 v[38:39], v[14:15], v[38:39] op_sel_hi:[0,1]
	v_pk_fma_f32 v[36:37], v[20:21], v[0:1], v[36:37] op_sel_hi:[1,0,1] neg_lo:[0,0,1] neg_hi:[0,0,1]
	v_pk_fma_f32 v[38:39], v[22:23], v[0:1], v[38:39] op_sel_hi:[1,0,1] neg_lo:[0,0,1] neg_hi:[0,0,1]
	v_fmac_f32_e32 v82, v36, v36
	v_pk_mul_f32 v[20:21], v[38:39], v[38:39]
	v_fmac_f32_e32 v82, v37, v37
	v_pk_mul_f32 v[40:41], v[40:41], v[80:81] op_sel_hi:[1,0]
	v_add_f32_e32 v20, v20, v82
	v_pk_mul_f32 v[42:43], v[42:43], v[80:81] op_sel_hi:[1,0]
	v_pk_mul_f32 v[40:41], v[14:15], v[40:41] op_sel_hi:[0,1]
	v_add_f32_e32 v68, v21, v20
	global_load_dwordx4 v[20:23], v166, s[2:3] offset:160
	v_pk_mul_f32 v[42:43], v[14:15], v[42:43] op_sel_hi:[0,1]
	v_pk_fma_f32 v[40:41], v[24:25], v[0:1], v[40:41] op_sel_hi:[1,0,1] neg_lo:[0,0,1] neg_hi:[0,0,1]
	v_pk_fma_f32 v[42:43], v[26:27], v[0:1], v[42:43] op_sel_hi:[1,0,1] neg_lo:[0,0,1] neg_hi:[0,0,1]
	v_pk_mul_f32 v[26:27], v[40:41], v[40:41]
	v_pk_mul_f32 v[24:25], v[42:43], v[42:43]
	v_add_f32_e32 v26, v26, v68
	v_add_f32_e32 v26, v27, v26
	v_add_f32_e32 v24, v24, v26
	v_add_f32_e32 v68, v25, v24
	global_load_dwordx4 v[24:27], v166, s[2:3] offset:192
	v_pk_mul_f32 v[44:45], v[44:45], v[80:81] op_sel_hi:[1,0]
	v_pk_mul_f32 v[46:47], v[46:47], v[80:81] op_sel_hi:[1,0]
	v_pk_mul_f32 v[44:45], v[14:15], v[44:45] op_sel_hi:[0,1]
	v_pk_mul_f32 v[46:47], v[14:15], v[46:47] op_sel_hi:[0,1]
	v_pk_fma_f32 v[28:29], v[28:29], v[0:1], v[44:45] op_sel_hi:[1,0,1] neg_lo:[0,0,1] neg_hi:[0,0,1]
	v_pk_fma_f32 v[30:31], v[30:31], v[0:1], v[46:47] op_sel_hi:[1,0,1] neg_lo:[0,0,1] neg_hi:[0,0,1]
	v_pk_mul_f32 v[46:47], v[28:29], v[28:29]
	v_pk_mul_f32 v[44:45], v[30:31], v[30:31]
	v_add_f32_e32 v0, v46, v68
	v_add_f32_e32 v0, v47, v0
	v_add_f32_e32 v0, v44, v0
	v_add_f32_e32 v0, v45, v0
	ds_bpermute_b32 v14, v167, v0
	s_waitcnt lgkmcnt(0)
	v_add_f32_e32 v0, v0, v14
	v_fmamk_f32 v0, v0, 0x3c800000, v213
	v_cmp_gt_f32_e32 vcc, s54, v0
	v_mul_f32_e32 v14, 0x4b800000, v0
	s_nop 0
	v_cndmask_b32_e32 v0, v0, v14, vcc
	v_rsq_f32_e32 v0, v0
	s_nop 0
	v_mul_f32_e32 v14, 0x45800000, v0
	v_cndmask_b32_e32 v0, v0, v14, vcc
	v_mul_f32_e32 v14, v233, v0
	v_pk_mul_f32 v[46:47], v[66:67], v[14:15] op_sel_hi:[1,0]
	v_pk_mul_f32 v[44:45], v[64:65], v[14:15] op_sel_hi:[1,0]
	s_waitcnt vmcnt(6)
	v_pk_mul_f32 v[2:3], v[2:3], v[46:47]
	v_pk_mul_f32 v[4:5], v[4:5], v[44:45]
	v_bfe_u32 v45, v3, 16, 1
	v_bfe_u32 v46, v2, 16, 1
	v_bfe_u32 v0, v5, 16, 1
	v_bfe_u32 v44, v4, 16, 1
	v_add3_u32 v2, v2, v46, s37
	v_add3_u32 v45, v3, v45, s37
	v_add3_u32 v3, v4, v44, s37
	v_add3_u32 v0, v5, v0, s37
	v_perm_b32 v2, v45, v2, s0
	v_pk_mul_f32 v[4:5], v[54:55], v[14:15] op_sel_hi:[1,0]
	v_pk_mul_f32 v[44:45], v[52:53], v[14:15] op_sel_hi:[1,0]
	s_waitcnt vmcnt(5)
	v_pk_mul_f32 v[4:5], v[8:9], v[4:5]
	v_pk_mul_f32 v[6:7], v[6:7], v[44:45]
	v_perm_b32 v3, v0, v3, s0
	v_bfe_u32 v0, v5, 16, 1
	v_bfe_u32 v8, v4, 16, 1
	v_bfe_u32 v9, v7, 16, 1
	v_bfe_u32 v44, v6, 16, 1
	v_add3_u32 v6, v6, v44, s37
	v_add3_u32 v7, v7, v9, s37
	v_add3_u32 v4, v4, v8, s37
	v_add3_u32 v0, v5, v0, s37
	v_perm_b32 v5, v0, v4, s0
	v_perm_b32 v4, v7, v6, s0
	v_add_u32_e32 v0, 0x9800, v81
	ds_write2_b64 v0, v[2:3], v[4:5] offset1:2
	v_pk_mul_f32 v[2:3], v[58:59], v[14:15] op_sel_hi:[1,0]
	v_pk_mul_f32 v[4:5], v[56:57], v[14:15] op_sel_hi:[1,0]
	s_waitcnt vmcnt(4)
	v_pk_mul_f32 v[2:3], v[12:13], v[2:3]
	v_pk_mul_f32 v[4:5], v[10:11], v[4:5]
	v_bfe_u32 v6, v3, 16, 1
	v_bfe_u32 v7, v2, 16, 1
	v_bfe_u32 v8, v5, 16, 1
	v_bfe_u32 v9, v4, 16, 1
	v_add3_u32 v4, v4, v9, s37
	v_add3_u32 v5, v5, v8, s37
	v_add3_u32 v2, v2, v7, s37
	v_add3_u32 v3, v3, v6, s37
	v_perm_b32 v3, v3, v2, s0
	v_perm_b32 v2, v5, v4, s0
	v_pk_mul_f32 v[4:5], v[62:63], v[14:15] op_sel_hi:[1,0]
	v_pk_mul_f32 v[6:7], v[60:61], v[14:15] op_sel_hi:[1,0]
	s_waitcnt vmcnt(3)
	v_pk_mul_f32 v[4:5], v[50:51], v[4:5]
	v_pk_mul_f32 v[6:7], v[48:49], v[6:7]
	v_bfe_u32 v8, v5, 16, 1
	v_bfe_u32 v9, v4, 16, 1
	v_bfe_u32 v10, v7, 16, 1
	v_bfe_u32 v11, v6, 16, 1
	v_add3_u32 v6, v6, v11, s37
	v_add3_u32 v7, v7, v10, s37
	v_add3_u32 v4, v4, v9, s37
	v_add3_u32 v5, v5, v8, s37
	v_perm_b32 v5, v5, v4, s0
	v_perm_b32 v4, v7, v6, s0
	ds_write2_b64 v0, v[2:3], v[4:5] offset0:4 offset1:6
	v_pk_mul_f32 v[2:3], v[34:35], v[14:15] op_sel_hi:[1,0]
	v_pk_mul_f32 v[4:5], v[32:33], v[14:15] op_sel_hi:[1,0]
	s_waitcnt vmcnt(2)
	v_pk_mul_f32 v[2:3], v[18:19], v[2:3]
	v_pk_mul_f32 v[4:5], v[16:17], v[4:5]
	v_bfe_u32 v6, v3, 16, 1
	v_bfe_u32 v7, v2, 16, 1
	v_bfe_u32 v8, v5, 16, 1
	v_bfe_u32 v9, v4, 16, 1
	v_add3_u32 v4, v4, v9, s37
	v_add3_u32 v5, v5, v8, s37
	v_add3_u32 v2, v2, v7, s37
	v_add3_u32 v3, v3, v6, s37
	v_perm_b32 v3, v3, v2, s0
	v_perm_b32 v2, v5, v4, s0
	v_pk_mul_f32 v[4:5], v[38:39], v[14:15] op_sel_hi:[1,0]
	v_pk_mul_f32 v[6:7], v[36:37], v[14:15] op_sel_hi:[1,0]
	s_waitcnt vmcnt(1)
	v_pk_mul_f32 v[4:5], v[22:23], v[4:5]
	v_pk_mul_f32 v[6:7], v[20:21], v[6:7]
	v_bfe_u32 v8, v5, 16, 1
	v_bfe_u32 v9, v4, 16, 1
	v_bfe_u32 v10, v7, 16, 1
	v_bfe_u32 v11, v6, 16, 1
	v_add3_u32 v6, v6, v11, s37
	v_add3_u32 v7, v7, v10, s37
	v_add3_u32 v4, v4, v9, s37
	v_add3_u32 v5, v5, v8, s37
	v_perm_b32 v5, v5, v4, s0
	v_perm_b32 v4, v7, v6, s0
	ds_write2_b64 v0, v[2:3], v[4:5] offset0:8 offset1:10
	v_pk_mul_f32 v[2:3], v[42:43], v[14:15] op_sel_hi:[1,0]
	v_pk_mul_f32 v[4:5], v[40:41], v[14:15] op_sel_hi:[1,0]
	s_waitcnt vmcnt(0)
	v_pk_mul_f32 v[2:3], v[26:27], v[2:3]
	v_pk_mul_f32 v[4:5], v[24:25], v[4:5]
	v_bfe_u32 v6, v3, 16, 1
	v_bfe_u32 v7, v2, 16, 1
	v_bfe_u32 v8, v5, 16, 1
	v_bfe_u32 v9, v4, 16, 1
	v_add3_u32 v4, v4, v9, s37
	v_add3_u32 v5, v5, v8, s37
	v_add3_u32 v2, v2, v7, s37
	v_add3_u32 v3, v3, v6, s37
	v_perm_b32 v7, v3, v2, s0
	v_perm_b32 v6, v5, v4, s0
	global_load_dwordx4 v[2:5], v166, s[2:3] offset:224
	v_pk_mul_f32 v[8:9], v[28:29], v[14:15] op_sel_hi:[1,0]
	v_pk_mul_f32 v[10:11], v[30:31], v[14:15] op_sel_hi:[1,0]
	s_waitcnt vmcnt(0)
	v_pk_mul_f32 v[2:3], v[8:9], v[2:3]
	v_pk_mul_f32 v[4:5], v[10:11], v[4:5]
	v_bfe_u32 v8, v3, 16, 1
	v_bfe_u32 v9, v2, 16, 1
	v_bfe_u32 v10, v5, 16, 1
	v_bfe_u32 v11, v4, 16, 1
	v_add3_u32 v4, v4, v11, s37
	v_add3_u32 v5, v5, v10, s37
	v_add3_u32 v2, v2, v9, s37
	v_add3_u32 v3, v3, v8, s37
	v_perm_b32 v2, v3, v2, s0
	v_perm_b32 v3, v5, v4, s0
	s_lshl_b32 s0, s12, 12
	s_or_b32 s0, s0, s11
	s_addk_i32 s0, 0x2000
	ds_write2_b64 v0, v[6:7], v[2:3] offset0:12 offset1:14
	v_add_u32_e32 v6, s0, v234
	v_lshrrev_b32_e32 v7, 3, v165
	v_lshlrev_b32_e32 v0, 1, v164
	s_lshl_b32 s0, s10, 7
	v_mul_u32_u24_e32 v2, 0x90, v7
	v_or_b32_e32 v6, v6, v7
	s_add_u32 s0, s94, s0
	v_add3_u32 v10, v15, v0, v2
	v_ashrrev_i32_e32 v7, 31, v6
	s_waitcnt lgkmcnt(0)
	s_barrier
	s_addc_u32 s1, s95, 0
	ds_read_b128 v[2:5], v10 offset:38912
	v_lshlrev_b64 v[8:9], 11, v[6:7]
	v_lshl_add_u64 v[8:9], s[0:1], 0, v[8:9]
	v_lshl_add_u64 v[8:9], v[8:9], 0, v[0:1]
	v_add_co_u32_e32 v8, vcc, s35, v8
	s_nop 1
	v_addc_co_u32_e32 v9, vcc, 0, v9, vcc
	s_waitcnt lgkmcnt(0)
	global_store_dwordx4 v[8:9], v[2:5], off offset:1280
	v_or_b32_e32 v8, 8, v6
	v_ashrrev_i32_e32 v9, 31, v8
	ds_read_b128 v[2:5], v10 offset:40064
	v_lshlrev_b64 v[8:9], 11, v[8:9]
	v_lshl_add_u64 v[8:9], s[0:1], 0, v[8:9]
	v_lshl_add_u64 v[8:9], v[8:9], 0, v[0:1]
	v_add_co_u32_e32 v8, vcc, s35, v8
	s_nop 1
	v_addc_co_u32_e32 v9, vcc, 0, v9, vcc
	s_waitcnt lgkmcnt(0)
	global_store_dwordx4 v[8:9], v[2:5], off offset:1280
	v_or_b32_e32 v8, 16, v6
	v_ashrrev_i32_e32 v9, 31, v8
	ds_read_b128 v[2:5], v10 offset:41216
	v_lshlrev_b64 v[8:9], 11, v[8:9]
	v_lshl_add_u64 v[8:9], s[0:1], 0, v[8:9]
	v_lshl_add_u64 v[8:9], v[8:9], 0, v[0:1]
	v_add_co_u32_e32 v8, vcc, s35, v8
	v_or_b32_e32 v6, 24, v6
	s_nop 0
	v_addc_co_u32_e32 v9, vcc, 0, v9, vcc
	v_ashrrev_i32_e32 v7, 31, v6
	s_waitcnt lgkmcnt(0)
	global_store_dwordx4 v[8:9], v[2:5], off offset:1280
	ds_read_b128 v[2:5], v10 offset:42368
	v_lshlrev_b64 v[6:7], 11, v[6:7]
	v_lshl_add_u64 v[6:7], s[0:1], 0, v[6:7]
	v_lshl_add_u64 v[6:7], v[6:7], 0, v[0:1]
	v_add_co_u32_e32 v6, vcc, 0x10885000, v6
	s_nop 1
	v_addc_co_u32_e32 v7, vcc, 0, v7, vcc
	s_waitcnt lgkmcnt(0)
	global_store_dwordx4 v[6:7], v[2:5], off offset:1280
	s_barrier
